# same_without_late_weight_transposes
# baseline (speedup 1.0000x reference)
; #define LAS __attribute__((address_space(3)))
; __device__ __forceinline__ void p0_transpose_item(const float* W, int N, int ksrc0, int nsrc0, const float* ksc, bf16_t* WT, int nrow0, int kdst0, LAS float* scr, int lane) {
; #pragma unroll 8
;     for (int i = 0; i < 32; ++i) { const int kk = 2 * i + (lane >> 5); float v = W[(size_t)(ksrc0 + kk) * N + nsrc0 + (lane & 31)]; if (ksc) v *= ksc[ksrc0 + kk]; scr[kk * 33 + (lane & 31)] = v; }
;     asm volatile("s_waitcnt lgkmcnt(0)" ::: "memory");
; __device__ __forceinline__ void xcd_barrier(const XcdBarrier& b) {
;     asm volatile("s_waitcnt vmcnt(0)" ::: "memory");
;     __syncthreads();
;     if (threadIdx.x == 0) {
;         unsigned* bar = b.bar;
;         __builtin_amdgcn_s_waitcnt(0);
;         unsigned nloc = b.st[0], nx = b.st[1];
;         if (nloc == 0u) { xcd_barrier_complete(bar, b.x, nloc, nx); b.st[0] = nloc; b.st[1] = nx; }
.Lwt_fast:
	v_lshl_add_u64 v[60:61], v[40:41], 0, s[16:17]
	global_load_dword v70, v[60:61], off
	v_lshl_add_u64 v[60:61], v[36:37], 0, s[16:17]
	global_load_dword v71, v[60:61], off
	v_lshl_add_u64 v[60:61], v[34:35], 0, s[16:17]
	global_load_dword v72, v[60:61], off
	v_lshl_add_u64 v[60:61], v[32:33], 0, s[16:17]
	global_load_dword v73, v[60:61], off
	v_lshl_add_u64 v[60:61], v[30:31], 0, s[16:17]
	global_load_dword v74, v[60:61], off
	v_lshl_add_u64 v[60:61], v[28:29], 0, s[16:17]
	global_load_dword v75, v[60:61], off
	v_lshl_add_u64 v[60:61], v[26:27], 0, s[16:17]
	global_load_dword v76, v[60:61], off
	v_lshl_add_u64 v[60:61], v[22:23], 0, s[16:17]
	global_load_dword v77, v[60:61], off
	v_lshl_add_u64 v[62:63], s[18:19], 0, v[38:39]
	global_load_dword v80, v[62:63], off
	v_lshl_add_u64 v[64:65], s[18:19], 0, v[24:25]
	global_load_dword v81, v[64:65], off offset:8
	global_load_dword v82, v[64:65], off offset:16
	global_load_dword v83, v[64:65], off offset:24
	global_load_dword v84, v[64:65], off offset:32
	global_load_dword v85, v[64:65], off offset:40
	global_load_dword v86, v[64:65], off offset:48
	global_load_dword v87, v[64:65], off offset:56
	s_waitcnt vmcnt(0)
	v_mul_f32_e32 v70, v70, v80
	v_mul_f32_e32 v71, v71, v81
	v_mul_f32_e32 v72, v72, v82
	v_mul_f32_e32 v73, v73, v83
	v_mul_f32_e32 v74, v74, v84
	v_mul_f32_e32 v75, v75, v85
	v_mul_f32_e32 v76, v76, v86
	v_mul_f32_e32 v77, v77, v87
	ds_write_b32 v2, v70
	ds_write_b32 v2, v71 offset:264
	ds_write_b32 v2, v72 offset:528
	ds_write_b32 v2, v73 offset:792
	ds_write_b32 v2, v74 offset:1056
	ds_write_b32 v2, v75 offset:1320
	ds_write_b32 v2, v76 offset:1584
	ds_write_b32 v2, v77 offset:1848
	s_add_u32 s16, s16, 0x54000
	s_addc_u32 s17, s17, 0
	s_add_u32 s18, s18, 64
	s_addc_u32 s19, s19, 0
	v_add_u32_e32 v2, 0x840, v2
	s_cmp_lg_u32 s16, 0x150000
	s_cbranch_scc1 .Lwt_fast
	s_branch .LBB0_44
.LBB0_106:
	s_cmp_gt_i32 s67, 1
	s_cselect_b64 s[0:1], -1, 0
	s_and_b64 s[4:5], s[4:5], s[0:1]
	s_andn2_b64 vcc, exec, s[4:5]
	s_cbranch_vccnz .LBB0_160
	s_getreg_b32 s6, hwreg(HW_REG_XCC_ID, 0, 4)
	s_waitcnt vmcnt(0)
	s_waitcnt lgkmcnt(0)
	s_barrier
	s_and_saveexec_b64 s[4:5], s[94:95]
	s_cbranch_execz .LBB0_159
	s_add_i32 s7, 0, 0x25fc0
	s_waitcnt vmcnt(15)
	v_mov_b32_e32 v0, s7
	s_waitcnt vmcnt(0) expcnt(0) lgkmcnt(0)
	ds_read_b32 v2, v0
	s_add_i32 s7, 0, 0x25fc4
	v_mov_b32_e32 v0, s7
	ds_read_b32 v0, v0
	s_and_b32 s33, s6, 15
	s_waitcnt lgkmcnt(1)
	v_cmp_ne_u32_e32 vcc, 0, v2
	s_cbranch_vccnz .LBB0_123
	s_load_dwordx2 s[10:11], s[74:75], 0x80
	s_load_dword s9, s[74:75], 0x88
	s_add_u32 s6, s64, 0xaf0200
	s_addc_u32 s7, s65, 0
	s_add_u32 s8, s64, 0xaf0400
	s_waitcnt lgkmcnt(0)
	s_mul_i32 s49, s11, s10
	s_mul_i32 s49, s49, s9
	s_addc_u32 s9, s65, 0
	s_add_u32 s10, s64, 0xaf0500
	s_addc_u32 s11, s65, 0
	s_add_u32 s12, s64, 0xaf0600
	s_addc_u32 s13, s65, 0
	s_add_u32 s14, s64, 0xaf0700
	s_addc_u32 s15, s65, 0
	s_add_u32 s16, s64, 0xaf0800
	s_addc_u32 s17, s65, 0
	s_add_u32 s18, s64, 0xaf0900
	s_addc_u32 s19, s65, 0
	s_add_u32 s20, s64, 0xaf0a00
	s_addc_u32 s21, s65, 0
	s_add_u32 s22, s64, 0xaf0b00
	s_addc_u32 s23, s65, 0
	s_add_u32 s24, s64, 0xaf0c00
	s_addc_u32 s25, s65, 0
	s_add_u32 s26, s64, 0xaf0d00
	s_addc_u32 s27, s65, 0
	s_add_u32 s28, s64, 0xaf0e00
	s_addc_u32 s29, s65, 0
	s_add_u32 s30, s64, 0xaf0f00
	s_addc_u32 s31, s65, 0
	s_add_u32 s34, s64, 0xaf1000
	s_addc_u32 s35, s65, 0
	s_add_u32 s36, s64, 0xaf1100
	s_addc_u32 s37, s65, 0
	s_add_u32 s38, s64, 0xaf1200
	s_addc_u32 s39, s65, 0
	s_add_u32 s40, s64, 0xaf1300
	s_addc_u32 s41, s65, 0
	s_mov_b32 s50, 1
	v_mov_b32_e32 v16, 0
	s_branch .LBB0_111
